# v114 + mixer queue pull-ahead: a workgroup starting a conv item requests its next queue index right away so the atomic round trip overlaps the item
# baseline (speedup 1.0000x reference)
; #define LAS __attribute__((address_space(3)))
; __device__ __forceinline__ unsigned xb_add(unsigned* p, unsigned v) { return __hip_atomic_fetch_add(p, v, __ATOMIC_RELAXED, __HIP_MEMORY_SCOPE_AGENT); }
; __device__ __forceinline__ unsigned xb_xcc_id() { return (unsigned)__builtin_amdgcn_s_getreg((3 << 11) | 20) & 0xFu; }
; __device__ __forceinline__ XcdBarrier xcd_barrier_post(unsigned* bar, volatile LAS unsigned* st) {
;     XcdBarrier b; b.bar = bar; b.x = xb_xcc_id(); b.st = st;
;     if (threadIdx.x == 0) (void)xb_add(&bar[XB_XCNT(b.x)], 1u);
;     return b;
; __global__ void __launch_bounds__(512, 2) fwd_megakernel(Args a) {
;     extern __shared__ __attribute__((aligned(16))) unsigned char lds_raw[];
;     LAS unsigned char* lds = (LAS unsigned char*)lds_raw;
;     cg::grid_group grid = cg::this_grid();
;     const int bid = blockIdx.x, G = gridDim.x;
;     if (threadIdx.x < 64) ((LAS unsigned*)(lds + 131072))[threadIdx.x] = 0u;
;     __syncthreads();
;     (void)xcd_barrier_post((unsigned*)(a.ws + WS_BAR), (volatile LAS unsigned*)(lds + 131072) + 8);
_Z14fwd_megakernel4Args:
	s_load_dwordx4 s[76:79], s[0:1], 0x80
	s_load_dwordx2 s[42:43], s[0:1], 0x90
	s_add_u32 s6, s0, 0x90
	v_and_b32_e32 v208, 0x3ff, v0
	s_mov_b32 s71, s2
	s_addc_u32 s7, s1, 0
	v_cmp_gt_u32_e32 vcc, 64, v208
	s_and_saveexec_b64 s[4:5], vcc
	v_lshl_add_u32 v1, v208, 2, 0
	v_add_u32_e32 v1, 0x20000, v1
	v_mov_b32_e32 v2, 0
	ds_write_b32 v1, v2
	s_or_b64 exec, exec, s[4:5]
	s_load_dword s2, s[0:1], 0x98
	s_waitcnt lgkmcnt(0)
	s_mov_b32 s4, 0
	s_nop 0
	v_writelane_b32 v255, s4, 41
	s_add_u32 s4, s78, 0x1700000
	s_addc_u32 s5, s79, 0
	v_writelane_b32 v253, s4, 0
	s_barrier
	s_nop 0
	v_writelane_b32 v253, s5, 1
	s_getreg_b32 s3, hwreg(HW_REG_XCC_ID, 0, 4)
	v_cmp_eq_u32_e64 s[8:9], 0, v208
	s_mov_b64 s[4:5], exec
	s_nop 0
	v_writelane_b32 v253, s8, 2
	s_nop 1
	v_writelane_b32 v253, s9, 3
	s_and_b64 s[8:9], s[4:5], s[8:9]
	s_mov_b64 exec, s[8:9]
	s_cbranch_execz .LBB0_5
	s_mov_b64 s[8:9], exec
	v_mbcnt_lo_u32_b32 v1, s8, 0
	v_mbcnt_hi_u32_b32 v1, s9, v1
	v_cmp_eq_u32_e32 vcc, 0, v1
	s_and_b64 s[10:11], exec, vcc
	s_mov_b64 exec, s[10:11]
	s_cbranch_execz .LBB0_5
	s_lshl_b32 s3, s3, 8
	s_bcnt1_i32_b64 s8, s[8:9]
	s_and_b32 s3, s3, 0xf00
	v_mov_b32_e32 v2, s8
	v_readlane_b32 s8, v253, 0
	v_mov_b32_e32 v1, s3
	v_readlane_b32 s9, v253, 1
	s_nop 4
	global_atomic_add v1, v2, s[8:9] offset:1024

; __device__ __forceinline__ void p_mixer(const Args& a, int l, LAS unsigned char* lds, int tid, int lane, int wave, int bid, int G) {
;     ...
;         if (threadIdx.x == 0) slot[0] = __hip_atomic_fetch_add(head, 1u, __ATOMIC_RELAXED, __HIP_MEMORY_SCOPE_AGENT);
;         __syncthreads();
;         const int q = (int)slot[0];
;         __syncthreads();
;         if (q >= N_AS + N_CV) { queue_empty = true; continue; }
.Lq_dyn128:
	v_readlane_b32 s6, v255, 41
	s_nop 3
	s_cmp_eq_u32 s6, 1
	s_cbranch_scc1 .Lpa_have
	global_atomic_add v1, v173, v1, s[2:3] sc0
	s_waitcnt vmcnt(0)
	v_add_u32_e32 v1, 0x80, v1
	s_branch .LBB0_450
.Lpa_have:
	s_waitcnt vmcnt(0)
	v_add_u32_e32 v1, 0x80, v241
	s_branch .LBB0_450

; __device__ __forceinline__ void conv_item(const Args& a, int l, int it, int lane, int wave) {
;     const bf16_t* proj = (const bf16_t*)(a.ws + WS_PROJ); bf16_t* Y = (bf16_t*)(a.ws + WS_H);
;     const int t0 = it * 64 + wave * 8, ch = lane * 8;
;     const float* cw = a.in[11] + (size_t)l * 3 * 512 + ch;
;     float w0[8], w1[8], w2[8];
;     { const f32x4 a0 = *(const f32x4*)(cw), a1 = *(const f32x4*)(cw + 4), b0 = *(const f32x4*)(cw + 512), b1 = *(const f32x4*)(cw + 516), c0 = *(const f32x4*)(cw + 1024), c1 = *(const f32x4*)(cw + 1028);
;       w0[0] = a0.x; w0[1] = a0.y; w0[2] = a0.z; w0[3] = a0.w; w0[4] = a1.x; w0[5] = a1.y; w0[6] = a1.z; w0[7] = a1.w;
;       w1[0] = b0.x; w1[1] = b0.y; w1[2] = b0.z; w1[3] = b0.w; w1[4] = b1.x; w1[5] = b1.y; w1[6] = b1.z; w1[7] = b1.w;
;       w2[0] = c0.x; w2[1] = c0.y; w2[2] = c0.z; w2[3] = c0.w; w2[4] = c1.x; w2[5] = c1.y; w2[6] = c1.z; w2[7] = c1.w; }
;     u32x4 uw[8], gw[8];
; #pragma unroll
;     for (int i = 0; i < 8; ++i) { uw[i] = *(const u32x4*)(proj + (size_t)(t0 + i) * PO2 + C_U + ch); gw[i] = *(const u32x4*)(proj + (size_t)(t0 + i) * PO2 + C_GZ + ch); }
; __device__ __forceinline__ void p_mixer(const Args& a, int l, LAS unsigned char* lds, int tid, int lane, int wave, int bid, int G) {
;     ...
;         const int q = (int)slot[0];
;         __syncthreads();
;         if (q >= N_AS + N_CV) { queue_empty = true; continue; }
;         ++pulled;
;         asm volatile("" : "+v"(tid)); lane = tid & 63;
;         if (q < N_AS) attn_sample_item(a, l, q, lds, tid, lane, wave);
;         else conv_item(a, l, q - N_AS, lane, wave);
.LBB0_451:
	s_or_b64 exec, exec, s[0:1]
	s_mov_b32 s4, 0
	s_nop 0
	v_writelane_b32 v255, s4, 41
	v_readlane_b32 s0, v254, 46
	s_waitcnt lgkmcnt(0)
	s_barrier
	v_mov_b32_e32 v0, s0
	ds_read_b32 v0, v0
	s_movk_i32 s0, 0x18f
	s_mov_b64 s[68:69], -1
	s_waitcnt lgkmcnt(0)
	s_barrier
	v_cmp_lt_i32_e32 vcc, s0, v0
	v_readfirstlane_b32 s36, v0
	s_cbranch_vccnz .LBB0_533
	s_mov_b64 s[0:1], -1
	v_and_b32_e32 v108, 63, v130
	s_cmpk_gt_i32 s36, 0x7f
	v_lshlrev_b32_e32 v109, 3, v108
	v_lshlrev_b32_e32 v110, 4, v108
	s_cbranch_scc0 .LBB0_503
	s_cmp_lg_u32 s42, 0x100
	s_cbranch_scc1 .Lpa_skip
	v_cmp_eq_u32_e32 vcc, 0, v208
	s_and_saveexec_b64 s[4:5], vcc
	s_cbranch_execz .Lpa_none
	v_readlane_b32 s2, v255, 15
	v_readlane_b32 s3, v255, 16
	s_nop 4
	global_atomic_add v241, v173, v212, s[2:3] sc0
.Lpa_none:
	s_or_b64 exec, exec, s[4:5]
	s_mov_b32 s2, 1
	s_nop 0
	v_writelane_b32 v255, s2, 41
.Lpa_skip:
	s_lshl_b32 s0, s36, 6
	v_readlane_b32 s1, v255, 17
	v_readlane_b32 s2, v255, 31
	s_add_i32 s0, s1, s0
	v_lshlrev_b32_e32 v172, 5, v108
	v_readlane_b32 s3, v255, 32
	s_ashr_i32 s1, s0, 31
	s_mul_i32 s4, s0, 0x1200
	v_lshl_add_u64 v[8:9], s[2:3], 0, v[172:173]
	v_lshl_add_u64 v[10:11], v[8:9], 0, s[26:27]
	v_add_co_u32_e32 v8, vcc, 0x1000, v8
	s_mul_hi_i32 s5, s0, 0x1200
	s_add_u32 s4, s74, s4
	v_addc_co_u32_e32 v9, vcc, 0, v9, vcc
	s_addc_u32 s5, s75, s5
	s_or_b32 s34, s0, 1
	global_load_dwordx4 v[0:3], v172, s[2:3] offset:16
	global_load_dwordx4 v[12:15], v172, s[2:3]
	global_load_dwordx4 v[4:7], v172, s[2:3] offset:2064
	global_load_dwordx4 v[16:19], v172, s[2:3] offset:2048
	global_load_dwordx4 v[20:23], v[8:9], off
	s_nop 0
	global_load_dwordx4 v[8:11], v[10:11], off offset:16
	s_nop 0
	global_load_dwordx4 v[84:87], v110, s[4:5]
	global_load_dwordx4 v[80:83], v110, s[4:5] offset:1024
	s_mul_i32 s4, s34, 0x1200
	s_mul_hi_i32 s5, s34, 0x1200
	s_add_u32 s4, s74, s4
	s_addc_u32 s5, s75, s5
	s_or_b32 s2, s0, 2
	global_load_dwordx4 v[76:79], v110, s[4:5]
	global_load_dwordx4 v[72:75], v110, s[4:5] offset:1024
	s_mul_i32 s4, s2, 0x1200
	s_mul_hi_i32 s5, s2, 0x1200
	s_add_u32 s4, s74, s4
	s_addc_u32 s5, s75, s5
	s_or_b32 s14, s0, 3
	global_load_dwordx4 v[68:71], v110, s[4:5]
	global_load_dwordx4 v[64:67], v110, s[4:5] offset:1024
	s_mul_i32 s4, s14, 0x1200
	s_mul_hi_i32 s5, s14, 0x1200
	s_add_u32 s4, s74, s4
	s_addc_u32 s5, s75, s5
	s_or_b32 s12, s0, 4
	global_load_dwordx4 v[60:63], v110, s[4:5]
	global_load_dwordx4 v[56:59], v110, s[4:5] offset:1024
	s_mul_i32 s4, s12, 0x1200
	s_mul_hi_i32 s5, s12, 0x1200
	s_add_u32 s4, s74, s4
	s_addc_u32 s5, s75, s5
	s_or_b32 s10, s0, 5
	global_load_dwordx4 v[52:55], v110, s[4:5]
	global_load_dwordx4 v[48:51], v110, s[4:5] offset:1024
	s_mul_i32 s4, s10, 0x1200
	s_mul_hi_i32 s5, s10, 0x1200
	s_add_u32 s4, s74, s4
	s_addc_u32 s5, s75, s5
	s_or_b32 s8, s0, 6
	global_load_dwordx4 v[44:47], v110, s[4:5]
	global_load_dwordx4 v[40:43], v110, s[4:5] offset:1024
	s_mul_i32 s4, s8, 0x1200
	s_mul_hi_i32 s5, s8, 0x1200
	s_add_u32 s4, s74, s4
	s_addc_u32 s5, s75, s5
	global_load_dwordx4 v[36:39], v110, s[4:5]
	global_load_dwordx4 v[32:35], v110, s[4:5] offset:1024
	s_or_b32 s4, s0, 7
	s_mul_i32 s6, s4, 0x1200
	s_mul_hi_i32 s5, s4, 0x1200
	s_add_u32 s6, s74, s6
	s_addc_u32 s7, s75, s5
	global_load_dwordx4 v[28:31], v110, s[6:7]
	global_load_dwordx4 v[24:27], v110, s[6:7] offset:1024
	s_cmpk_gt_i32 s0, 0x3fff
	s_cselect_b64 s[6:7], -1, 0
	s_mov_b64 s[20:21], -1
	s_and_b64 vcc, exec, s[6:7]
	v_lshlrev_b32_e32 v104, 2, v109
	s_cbranch_vccz .LBB0_455
	s_add_i32 s5, s0, 0xffffc000
	s_lshr_b32 s5, s5, 2
	v_readlane_b32 s3, v255, 18
	s_add_i32 s86, s5, s3
	v_readlane_b32 s16, v253, 4
	s_lshl_b64 s[38:39], s[86:87], 11
	v_readlane_b32 s20, v253, 8
	v_readlane_b32 s24, v253, 12
	v_readlane_b32 s21, v253, 9
	v_readlane_b32 s25, v253, 13
	s_add_u32 s20, s24, s38
	s_addc_u32 s21, s25, s39
	s_nop 1
	global_load_dwordx4 v[100:103], v104, s[20:21]
	global_load_dwordx4 v[96:99], v104, s[20:21] offset:16
	global_load_dwordx4 v[92:95], v104, s[20:21] offset:2048
	global_load_dwordx4 v[88:91], v104, s[20:21] offset:2064
	v_readlane_b32 s26, v253, 14
	v_readlane_b32 s27, v253, 15
	v_readlane_b32 s17, v253, 5
	v_readlane_b32 s18, v253, 6
	v_readlane_b32 s19, v253, 7
	v_readlane_b32 s22, v253, 10
	v_readlane_b32 s23, v253, 11
	v_readlane_b32 s28, v253, 16
	v_readlane_b32 s29, v253, 17
	v_readlane_b32 s30, v253, 18
	v_readlane_b32 s31, v253, 19
	s_mov_b64 s[26:27], 0x1000
	s_mov_b64 s[20:21], 0
